# SB unit prologue: Q row loads issued behind the first tile's four LDS-DMA pieces instead of ahead of all twelve
# speedup vs baseline: 1.0051x; 1.0006x over previous
.LBB0_332:
	s_or_b64 exec, exec, s[2:3]
	s_waitcnt lgkmcnt(0)
	s_barrier
	ds_read_b32 v0, v229
	s_movk_i32 s2, 0x3ff
	s_waitcnt lgkmcnt(0)
	v_cmp_lt_i32_e32 vcc, s2, v0
	v_readfirstlane_b32 s97, v0
	s_mov_b64 s[2:3], -1
	s_cbranch_vccnz .LBB0_301
	s_cmpk_gt_i32 s97, 0x1ff
	s_cbranch_scc0 .LBB0_385
	s_add_i32 s2, s97, 0xfffffe00
	s_lshr_b32 s99, s2, 6
	s_sub_i32 s6, 7, s99
	s_bfe_u32 s3, s97, 0x30003
	s_lshl_b32 s66, s6, 8
	v_readlane_b32 s2, v254, 53
	s_and_b32 s4, s97, 7
	s_add_i32 s66, s66, s2
	s_lshl_b32 s2, s3, 21
	v_mov_b32_e32 v82, v231
	v_writelane_b32 v255, s3, 49
	s_add_u32 s2, s78, s2
	s_addc_u32 s3, s79, 0
	v_and_b32_e32 v3, 31, v82
	v_writelane_b32 v255, s4, 50
	s_lshl_b32 s4, s4, 18
	v_ashrrev_i32_e32 v2, 5, v82
	v_or_b32_e32 v0, s66, v3
	s_add_u32 s2, s2, s4
	s_addc_u32 s3, s3, 0
	v_lshlrev_b64 v[4:5], 7, v[0:1]
	v_lshlrev_b32_e32 v114, 3, v2
	v_lshl_add_u64 v[4:5], s[2:3], 0, v[4:5]
	v_ashrrev_i32_e32 v115, 31, v114
	v_lshl_add_u64 v[4:5], v[114:115], 1, v[4:5]
	v_mov_b32_e32 v190, v4
	v_mov_b32_e32 v191, v5
	v_cmp_gt_i32_e32 vcc, 2, v82
	s_and_saveexec_b64 s[4:5], vcc
	v_lshl_add_u32 v4, v82, 5, s94
	ds_write_b32 v4, v1
	s_or_b64 exec, exec, s[4:5]
	v_ashrrev_i32_e32 v4, 3, v82
	v_readlane_b32 s4, v254, 54
	v_mov_b32_e32 v7, v1
	v_mov_b32_e32 v9, v1
	v_add_u32_e32 v4, s4, v4
	v_lshrrev_b32_e32 v5, 1, v4
	v_xor_b32_e32 v6, v5, v82
	v_lshlrev_b32_e32 v4, 6, v4
	v_ashrrev_i32_e32 v5, 31, v4
	v_lshlrev_b32_e32 v6, 4, v6
	v_lshl_add_u64 v[4:5], v[4:5], 1, s[2:3]
	v_and_b32_e32 v6, 0x70, v6
	v_lshl_add_u64 v[4:5], v[4:5], 0, v[6:7]
	s_mov_b64 s[4:5], 0x1000000
	v_lshl_add_u64 v[116:117], v[4:5], 0, s[4:5]
	v_add_u32_e32 v5, s30, v114
	v_lshrrev_b32_e32 v4, 2, v82
	v_and_or_b32 v5, v4, 7, v5
	v_lshlrev_b32_e32 v6, 3, v82
	v_and_b32_e32 v126, 24, v6
	v_lshlrev_b32_e32 v6, 6, v5
	v_ashrrev_i32_e32 v7, 31, v6
	v_lshl_add_u64 v[6:7], v[6:7], 1, s[2:3]
	v_lshlrev_b32_e32 v8, 1, v126
	v_lshl_add_u64 v[6:7], v[6:7], 0, v[8:9]
	s_mov_b64 s[4:5], 0x2000000
	v_lshl_add_u64 v[118:119], v[6:7], 0, s[4:5]
	s_lshl_b32 s4, s6, 2
	s_add_i32 s80, s0, s4
	s_add_i32 s4, s80, 1
	s_mov_b32 s5, s81
	s_lshl_b64 s[6:7], s[4:5], 13
	v_lshl_add_u64 v[6:7], v[116:117], 0, s[6:7]
	s_mov_b64 s[10:11], 0x1000
	v_readlane_b32 s8, v255, 8
	s_mov_b32 s5, m0
	s_mov_b32 m0, s8
	s_nop 0
	global_load_lds_dwordx4 v[6:7], off
	s_mov_b32 m0, s5
	v_lshl_add_u64 v[6:7], v[6:7], 0, s[10:11]
	v_readlane_b32 s8, v254, 56
	s_mov_b32 s5, m0
	s_mov_b32 m0, s8
	s_nop 0
	global_load_lds_dwordx4 v[6:7], off
	s_mov_b32 m0, s5
	v_lshl_add_u64 v[6:7], v[118:119], 0, s[6:7]
	v_readlane_b32 s6, v254, 57
	s_mov_b32 s5, m0
	s_mov_b32 m0, s6
	s_nop 0
	global_load_lds_dwordx4 v[6:7], off
	s_mov_b32 m0, s5
	v_readlane_b32 s6, v254, 58
	v_lshl_add_u64 v[6:7], v[6:7], 0, 64
	s_mov_b32 s5, m0
	s_mov_b32 m0, s6
	s_nop 0
	global_load_lds_dwordx4 v[6:7], off
	s_mov_b32 m0, s5
	global_load_dwordx4 v[98:101], v[190:191], off
	global_load_dwordx4 v[102:105], v[190:191], off offset:32
	global_load_dwordx4 v[106:109], v[190:191], off offset:64
	global_load_dwordx4 v[110:113], v[190:191], off offset:96
	s_lshl_b64 s[6:7], s[80:81], 13
	v_lshl_add_u64 v[6:7], v[116:117], 0, s[6:7]
	v_readlane_b32 s8, v254, 59
	s_mov_b32 s5, m0
	s_mov_b32 m0, s8
	s_nop 0
	global_load_lds_dwordx4 v[6:7], off
	s_mov_b32 m0, s5
	v_lshl_add_u64 v[6:7], v[6:7], 0, s[10:11]
	v_readlane_b32 s8, v254, 60
	s_mov_b32 s5, m0
	s_mov_b32 m0, s8
	s_nop 0
	global_load_lds_dwordx4 v[6:7], off
	s_mov_b32 m0, s5
	v_lshl_add_u64 v[6:7], v[118:119], 0, s[6:7]
	v_readlane_b32 s6, v254, 61
	s_mov_b32 s5, m0
	s_mov_b32 m0, s6
	s_nop 0
	global_load_lds_dwordx4 v[6:7], off
	s_mov_b32 m0, s5
	v_lshl_add_u64 v[6:7], v[6:7], 0, 64
	v_readlane_b32 s8, v254, 62
	s_mov_b32 s5, m0
	s_mov_b32 m0, s8
	s_nop 0
	global_load_lds_dwordx4 v[6:7], off
	s_mov_b32 m0, s5
	s_cmp_lg_u32 s4, 1
	s_mov_b64 s[78:79], 0x1000
	s_cselect_b64 s[6:7], -1, 0
	s_cmp_eq_u32 s4, 1
	s_cbranch_scc1 .LBB0_338
	s_add_i32 s80, s4, -2
	s_lshl_b64 s[8:9], s[80:81], 13
	v_lshl_add_u64 v[6:7], v[116:117], 0, s[8:9]
	v_readlane_b32 s10, v254, 63
	s_mov_b32 s5, m0
	s_mov_b32 m0, s10
	s_nop 0
	global_load_lds_dwordx4 v[6:7], off
	s_mov_b32 m0, s5
	v_lshl_add_u64 v[6:7], v[6:7], 0, s[78:79]
	v_readlane_b32 s10, v255, 0
	s_mov_b32 s5, m0
	s_mov_b32 m0, s10
	s_nop 0
	global_load_lds_dwordx4 v[6:7], off
	s_mov_b32 m0, s5
	v_lshl_add_u64 v[6:7], v[118:119], 0, s[8:9]
	v_readlane_b32 s8, v255, 1
	s_mov_b32 s5, m0
	s_mov_b32 m0, s8
	s_nop 0
	global_load_lds_dwordx4 v[6:7], off
	s_mov_b32 m0, s5
	v_lshl_add_u64 v[6:7], v[6:7], 0, 64
	v_readlane_b32 s8, v255, 2
	s_mov_b32 s5, m0
	s_mov_b32 m0, s8
	s_nop 0
	global_load_lds_dwordx4 v[6:7], off
	s_mov_b32 m0, s5
